# v68 plus: the two adjacent closing waits of every K-loop load segment merged into one s_waitcnt vmcnt(8) lgkmcnt(0)
# speedup vs baseline: 1.0061x; 1.0020x over previous
.LBB0_186:
	s_mov_b32 m0, s41
	s_add_u32 s54, s28, 0x80
	s_addc_u32 s55, s29, 0
	ds_read_b128 v[194:197], v193 offset:49152
	ds_read_b128 v[198:201], v193 offset:50176
	ds_read_b128 v[202:205], v193 offset:51200
	ds_read_b128 v[206:209], v193 offset:52224
	ds_read_b128 v[212:215], v193 offset:53248
	ds_read_b128 v[216:219], v193 offset:54272
	ds_read_b128 v[220:223], v193 offset:55296
	ds_read_b128 v[224:227], v193 offset:56320
	global_load_lds_dwordx4 v4, s[54:55]
	s_mov_b32 m0, s42
	s_add_u32 s6, s28, 0x80080
	s_addc_u32 s7, s29, 0
	global_load_lds_dwordx4 v2, s[54:55]
	s_mov_b32 m0, s45
	s_add_u32 s98, s30, 0xfff80080
	s_addc_u32 s99, s31, -1
	global_load_lds_dwordx4 v4, s[6:7]
	s_mov_b32 m0, s46
	s_nop 0
	global_load_lds_dwordx4 v2, s[6:7]
	s_mov_b32 m0, s43
	s_nop 0
	global_load_lds_dwordx4 v168, s[98:99]
	s_mov_b32 m0, s44
	s_nop 0
	global_load_lds_dwordx4 v166, s[98:99]
	s_waitcnt vmcnt(8) lgkmcnt(0)
	s_barrier
	v_mfma_f32_16x16x32_bf16 v[10:13], v[158:161], v[194:197], v[10:13]
	v_mfma_f32_16x16x32_bf16 v[18:21], v[162:165], v[194:197], v[18:21]
	v_mfma_f32_16x16x32_bf16 v[26:29], v[158:161], v[202:205], v[26:29]
	v_mfma_f32_16x16x32_bf16 v[34:37], v[162:165], v[202:205], v[34:37]
	v_mfma_f32_16x16x32_bf16 v[180:183], v[158:161], v[212:215], v[42:45]
	v_mfma_f32_16x16x32_bf16 v[184:187], v[162:165], v[212:215], v[50:53]
	v_mfma_f32_16x16x32_bf16 v[158:161], v[158:161], v[220:223], v[58:61]
	v_mfma_f32_16x16x32_bf16 v[162:165], v[162:165], v[220:223], v[66:69]
	v_mfma_f32_16x16x32_bf16 v[66:69], v[150:153], v[198:201], v[10:13]
	v_mfma_f32_16x16x32_bf16 v[58:61], v[154:157], v[198:201], v[18:21]
	v_mfma_f32_16x16x32_bf16 v[50:53], v[150:153], v[206:209], v[26:29]
	v_mfma_f32_16x16x32_bf16 v[42:45], v[154:157], v[206:209], v[34:37]
	v_mfma_f32_16x16x32_bf16 v[34:37], v[150:153], v[216:219], v[180:183]
	v_mfma_f32_16x16x32_bf16 v[26:29], v[154:157], v[216:219], v[184:187]
	v_mfma_f32_16x16x32_bf16 v[18:21], v[150:153], v[224:227], v[158:161]
	v_mfma_f32_16x16x32_bf16 v[10:13], v[154:157], v[224:227], v[162:165]
	v_mfma_f32_16x16x32_bf16 v[6:9], v[142:145], v[194:197], v[6:9]
	v_mfma_f32_16x16x32_bf16 v[14:17], v[146:149], v[194:197], v[14:17]
	v_mfma_f32_16x16x32_bf16 v[22:25], v[142:145], v[202:205], v[22:25]
	v_mfma_f32_16x16x32_bf16 v[30:33], v[146:149], v[202:205], v[30:33]
	v_mfma_f32_16x16x32_bf16 v[150:153], v[142:145], v[212:215], v[38:41]
	v_mfma_f32_16x16x32_bf16 v[154:157], v[146:149], v[212:215], v[46:49]
	v_mfma_f32_16x16x32_bf16 v[142:145], v[142:145], v[220:223], v[54:57]
	v_mfma_f32_16x16x32_bf16 v[146:149], v[146:149], v[220:223], v[62:65]
	v_mfma_f32_16x16x32_bf16 v[62:65], v[74:77], v[198:201], v[6:9]
	v_mfma_f32_16x16x32_bf16 v[54:57], v[138:141], v[198:201], v[14:17]
	v_mfma_f32_16x16x32_bf16 v[46:49], v[74:77], v[206:209], v[22:25]
	v_mfma_f32_16x16x32_bf16 v[38:41], v[138:141], v[206:209], v[30:33]
	v_mfma_f32_16x16x32_bf16 v[30:33], v[74:77], v[216:219], v[150:153]
	v_mfma_f32_16x16x32_bf16 v[22:25], v[138:141], v[216:219], v[154:157]
	v_mfma_f32_16x16x32_bf16 v[14:17], v[74:77], v[224:227], v[142:145]
	v_mfma_f32_16x16x32_bf16 v[6:9], v[138:141], v[224:227], v[146:149]
	s_barrier
	s_add_i32 s53, s53, 2
	s_add_u32 s26, s26, 0x100
	s_addc_u32 s27, s27, 0
	s_add_u32 s25, s25, 0x100
	s_addc_u32 s52, s52, 0
	s_cmp_gt_u32 s53, 29
	s_cbranch_scc1 .LBB0_191

.LBB0_189:
	s_add_u32 s30, s26, 0xfff80080
	s_addc_u32 s31, s27, -1
	s_and_b64 s[28:29], s[28:29], exec
	s_cselect_b32 s31, s19, s31
	s_cselect_b32 s30, s50, s30
	s_cselect_b32 s29, s17, s52
	s_cselect_b32 s28, s51, s25
	s_add_i32 s54, 0, 0x10000
	s_add_i32 s56, 0, 0x14000
	ds_read_b128 v[74:77], v238
	ds_read_b128 v[138:141], v238 offset:1024
	ds_read_b128 v[142:145], v238 offset:2048
	ds_read_b128 v[146:149], v238 offset:3072
	ds_read_b128 v[150:153], v238 offset:16384
	ds_read_b128 v[154:157], v238 offset:17408
	ds_read_b128 v[158:161], v238 offset:18432
	ds_read_b128 v[162:165], v238 offset:19456
	s_add_i32 m0, s33, 0xc000
	ds_read_b128 v[180:183], v193
	ds_read_b128 v[184:187], v193 offset:1024
	ds_read_b128 v[194:197], v193 offset:2048
	ds_read_b128 v[198:201], v193 offset:3072
	ds_read_b128 v[202:205], v193 offset:4096
	ds_read_b128 v[212:215], v193 offset:5120
	ds_read_b128 v[216:219], v193 offset:6144
	ds_read_b128 v[220:223], v193 offset:7168
	global_load_lds_dwordx4 v172, s[26:27]
	s_add_i32 m0, s33, 0xe000
	s_nop 0
	global_load_lds_dwordx4 v174, s[26:27]
	s_waitcnt vmcnt(8) lgkmcnt(0)
	s_barrier
	v_mfma_f32_16x16x32_bf16 v[134:137], v[74:77], v[180:183], v[134:137]
	v_mfma_f32_16x16x32_bf16 v[126:129], v[142:145], v[180:183], v[126:129]
	v_mfma_f32_16x16x32_bf16 v[118:121], v[74:77], v[194:197], v[118:121]
	v_mfma_f32_16x16x32_bf16 v[110:113], v[142:145], v[194:197], v[110:113]
	v_mfma_f32_16x16x32_bf16 v[102:105], v[74:77], v[202:205], v[102:105]
	v_mfma_f32_16x16x32_bf16 v[94:97], v[142:145], v[202:205], v[94:97]
	v_mfma_f32_16x16x32_bf16 v[86:89], v[74:77], v[216:219], v[86:89]
	v_mfma_f32_16x16x32_bf16 v[78:81], v[142:145], v[216:219], v[78:81]
	v_mfma_f32_16x16x32_bf16 v[134:137], v[138:141], v[184:187], v[134:137]
	v_mfma_f32_16x16x32_bf16 v[126:129], v[146:149], v[184:187], v[126:129]
	v_mfma_f32_16x16x32_bf16 v[118:121], v[138:141], v[198:201], v[118:121]
	v_mfma_f32_16x16x32_bf16 v[110:113], v[146:149], v[198:201], v[110:113]
	v_mfma_f32_16x16x32_bf16 v[102:105], v[138:141], v[212:215], v[102:105]
	v_mfma_f32_16x16x32_bf16 v[94:97], v[146:149], v[212:215], v[94:97]
	v_mfma_f32_16x16x32_bf16 v[86:89], v[138:141], v[220:223], v[86:89]
	v_mfma_f32_16x16x32_bf16 v[78:81], v[146:149], v[220:223], v[78:81]
	v_mfma_f32_16x16x32_bf16 v[130:133], v[150:153], v[180:183], v[130:133]
	v_mfma_f32_16x16x32_bf16 v[122:125], v[158:161], v[180:183], v[122:125]
	v_mfma_f32_16x16x32_bf16 v[114:117], v[150:153], v[194:197], v[114:117]
	v_mfma_f32_16x16x32_bf16 v[106:109], v[158:161], v[194:197], v[106:109]
	v_mfma_f32_16x16x32_bf16 v[98:101], v[150:153], v[202:205], v[98:101]
	v_mfma_f32_16x16x32_bf16 v[90:93], v[158:161], v[202:205], v[90:93]
	v_mfma_f32_16x16x32_bf16 v[82:85], v[150:153], v[216:219], v[82:85]
	v_mfma_f32_16x16x32_bf16 v[70:73], v[158:161], v[216:219], v[70:73]
	v_mfma_f32_16x16x32_bf16 v[130:133], v[154:157], v[184:187], v[130:133]
	v_mfma_f32_16x16x32_bf16 v[122:125], v[162:165], v[184:187], v[122:125]
	v_mfma_f32_16x16x32_bf16 v[114:117], v[154:157], v[198:201], v[114:117]
	v_mfma_f32_16x16x32_bf16 v[106:109], v[162:165], v[198:201], v[106:109]
	v_mfma_f32_16x16x32_bf16 v[98:101], v[154:157], v[212:215], v[98:101]
	v_mfma_f32_16x16x32_bf16 v[90:93], v[162:165], v[212:215], v[90:93]
	v_mfma_f32_16x16x32_bf16 v[82:85], v[154:157], v[220:223], v[82:85]
	v_mfma_f32_16x16x32_bf16 v[70:73], v[162:165], v[220:223], v[70:73]
	s_barrier
	s_add_i32 s54, s54, s35
	s_mov_b32 m0, s54
	ds_read_b128 v[194:197], v193 offset:16384
	ds_read_b128 v[198:201], v193 offset:17408
	ds_read_b128 v[202:205], v193 offset:18432
	ds_read_b128 v[212:215], v193 offset:19456
	ds_read_b128 v[216:219], v193 offset:20480
	ds_read_b128 v[220:223], v193 offset:21504
	ds_read_b128 v[224:227], v193 offset:22528
	ds_read_b128 v[228:231], v193 offset:23552
	global_load_lds_dwordx4 v4, s[28:29]
	s_add_i32 m0, s54, 0x2000
	s_add_u32 s54, s28, 0x80000
	s_addc_u32 s55, s29, 0
	global_load_lds_dwordx4 v2, s[28:29]
	s_add_i32 s56, s56, s35
	s_mov_b32 m0, s56
	s_nop 0
	global_load_lds_dwordx4 v4, s[54:55]
	s_add_i32 m0, s56, 0x2000
	s_nop 0
	global_load_lds_dwordx4 v2, s[54:55]
	s_mov_b32 m0, s33
	s_nop 0
	global_load_lds_dwordx4 v168, s[30:31]
	s_mov_b32 m0, s38
	s_nop 0
	global_load_lds_dwordx4 v166, s[30:31]
	s_waitcnt vmcnt(8) lgkmcnt(0)
	s_barrier
	v_mfma_f32_16x16x32_bf16 v[66:69], v[74:77], v[194:197], v[66:69]
	v_mfma_f32_16x16x32_bf16 v[58:61], v[142:145], v[194:197], v[58:61]
	v_mfma_f32_16x16x32_bf16 v[50:53], v[74:77], v[202:205], v[50:53]
	v_mfma_f32_16x16x32_bf16 v[42:45], v[142:145], v[202:205], v[42:45]
	v_mfma_f32_16x16x32_bf16 v[248:251], v[74:77], v[216:219], v[34:37]
	v_mfma_f32_16x16x32_bf16 v[206:209], v[142:145], v[216:219], v[26:29]
	v_mfma_f32_16x16x32_bf16 v[74:77], v[74:77], v[224:227], v[18:21]
	v_mfma_f32_16x16x32_bf16 v[142:145], v[142:145], v[224:227], v[10:13]
	v_mfma_f32_16x16x32_bf16 v[10:13], v[138:141], v[198:201], v[66:69]
	v_mfma_f32_16x16x32_bf16 v[18:21], v[146:149], v[198:201], v[58:61]
	v_mfma_f32_16x16x32_bf16 v[26:29], v[138:141], v[212:215], v[50:53]
	v_mfma_f32_16x16x32_bf16 v[34:37], v[146:149], v[212:215], v[42:45]
	v_mfma_f32_16x16x32_bf16 v[42:45], v[138:141], v[220:223], v[248:251]
	v_mfma_f32_16x16x32_bf16 v[50:53], v[146:149], v[220:223], v[206:209]
	v_mfma_f32_16x16x32_bf16 v[58:61], v[138:141], v[228:231], v[74:77]
	v_mfma_f32_16x16x32_bf16 v[66:69], v[146:149], v[228:231], v[142:145]
	v_mfma_f32_16x16x32_bf16 v[62:65], v[150:153], v[194:197], v[62:65]
	v_mfma_f32_16x16x32_bf16 v[54:57], v[158:161], v[194:197], v[54:57]
	v_mfma_f32_16x16x32_bf16 v[46:49], v[150:153], v[202:205], v[46:49]
	v_mfma_f32_16x16x32_bf16 v[38:41], v[158:161], v[202:205], v[38:41]
	v_mfma_f32_16x16x32_bf16 v[74:77], v[150:153], v[216:219], v[30:33]
	v_mfma_f32_16x16x32_bf16 v[138:141], v[158:161], v[216:219], v[22:25]
	v_mfma_f32_16x16x32_bf16 v[142:145], v[150:153], v[224:227], v[14:17]
	v_mfma_f32_16x16x32_bf16 v[146:149], v[158:161], v[224:227], v[6:9]
	v_mfma_f32_16x16x32_bf16 v[6:9], v[154:157], v[198:201], v[62:65]
	v_mfma_f32_16x16x32_bf16 v[14:17], v[162:165], v[198:201], v[54:57]
	v_mfma_f32_16x16x32_bf16 v[22:25], v[154:157], v[212:215], v[46:49]
	v_mfma_f32_16x16x32_bf16 v[30:33], v[162:165], v[212:215], v[38:41]
	v_mfma_f32_16x16x32_bf16 v[38:41], v[154:157], v[220:223], v[74:77]
	v_mfma_f32_16x16x32_bf16 v[46:49], v[162:165], v[220:223], v[138:141]
	v_mfma_f32_16x16x32_bf16 v[54:57], v[154:157], v[228:231], v[142:145]
	v_mfma_f32_16x16x32_bf16 v[62:65], v[162:165], v[228:231], v[146:149]
	s_barrier
	ds_read_b128 v[158:161], v238 offset:32768
	ds_read_b128 v[150:153], v238 offset:33792
	ds_read_b128 v[162:165], v238 offset:34816
	ds_read_b128 v[154:157], v238 offset:35840
	ds_read_b128 v[142:145], v238 offset:49152
	ds_read_b128 v[74:77], v238 offset:50176
	ds_read_b128 v[146:149], v238 offset:51200
	ds_read_b128 v[138:141], v238 offset:52224
	s_add_u32 s30, s30, 0x80000
	s_addc_u32 s31, s31, 0
	s_mov_b32 m0, s39
	ds_read_b128 v[194:197], v193 offset:32768
	ds_read_b128 v[198:201], v193 offset:33792
	ds_read_b128 v[202:205], v193 offset:34816
	ds_read_b128 v[206:209], v193 offset:35840
	ds_read_b128 v[212:215], v193 offset:36864
	ds_read_b128 v[216:219], v193 offset:37888
	ds_read_b128 v[220:223], v193 offset:38912
	ds_read_b128 v[224:227], v193 offset:39936
	global_load_lds_dwordx4 v168, s[30:31]
	s_mov_b32 m0, s40
	s_nop 0
	global_load_lds_dwordx4 v166, s[30:31]
	s_waitcnt vmcnt(8) lgkmcnt(0)
	s_barrier
	v_mfma_f32_16x16x32_bf16 v[134:137], v[158:161], v[194:197], v[134:137]
	v_mfma_f32_16x16x32_bf16 v[126:129], v[162:165], v[194:197], v[126:129]
	v_mfma_f32_16x16x32_bf16 v[118:121], v[158:161], v[202:205], v[118:121]
	v_mfma_f32_16x16x32_bf16 v[110:113], v[162:165], v[202:205], v[110:113]
	v_mfma_f32_16x16x32_bf16 v[102:105], v[158:161], v[212:215], v[102:105]
	v_mfma_f32_16x16x32_bf16 v[94:97], v[162:165], v[212:215], v[94:97]
	v_mfma_f32_16x16x32_bf16 v[86:89], v[158:161], v[220:223], v[86:89]
	v_mfma_f32_16x16x32_bf16 v[78:81], v[162:165], v[220:223], v[78:81]
	v_mfma_f32_16x16x32_bf16 v[134:137], v[150:153], v[198:201], v[134:137]
	v_mfma_f32_16x16x32_bf16 v[126:129], v[154:157], v[198:201], v[126:129]
	v_mfma_f32_16x16x32_bf16 v[118:121], v[150:153], v[206:209], v[118:121]
	v_mfma_f32_16x16x32_bf16 v[110:113], v[154:157], v[206:209], v[110:113]
	v_mfma_f32_16x16x32_bf16 v[102:105], v[150:153], v[216:219], v[102:105]
	v_mfma_f32_16x16x32_bf16 v[94:97], v[154:157], v[216:219], v[94:97]
	v_mfma_f32_16x16x32_bf16 v[86:89], v[150:153], v[224:227], v[86:89]
	v_mfma_f32_16x16x32_bf16 v[78:81], v[154:157], v[224:227], v[78:81]
	v_mfma_f32_16x16x32_bf16 v[130:133], v[142:145], v[194:197], v[130:133]
	v_mfma_f32_16x16x32_bf16 v[122:125], v[146:149], v[194:197], v[122:125]
	v_mfma_f32_16x16x32_bf16 v[114:117], v[142:145], v[202:205], v[114:117]
	v_mfma_f32_16x16x32_bf16 v[106:109], v[146:149], v[202:205], v[106:109]
	v_mfma_f32_16x16x32_bf16 v[98:101], v[142:145], v[212:215], v[98:101]
	v_mfma_f32_16x16x32_bf16 v[90:93], v[146:149], v[212:215], v[90:93]
	v_mfma_f32_16x16x32_bf16 v[82:85], v[142:145], v[220:223], v[82:85]
	v_mfma_f32_16x16x32_bf16 v[70:73], v[146:149], v[220:223], v[70:73]
	v_mfma_f32_16x16x32_bf16 v[130:133], v[74:77], v[198:201], v[130:133]
	v_mfma_f32_16x16x32_bf16 v[122:125], v[138:141], v[198:201], v[122:125]
	v_mfma_f32_16x16x32_bf16 v[114:117], v[74:77], v[206:209], v[114:117]
	v_mfma_f32_16x16x32_bf16 v[106:109], v[138:141], v[206:209], v[106:109]
	v_mfma_f32_16x16x32_bf16 v[98:101], v[74:77], v[216:219], v[98:101]
	v_mfma_f32_16x16x32_bf16 v[90:93], v[138:141], v[216:219], v[90:93]
	v_mfma_f32_16x16x32_bf16 v[82:85], v[74:77], v[224:227], v[82:85]
	v_mfma_f32_16x16x32_bf16 v[70:73], v[138:141], v[224:227], v[70:73]
	s_barrier
	s_and_b64 vcc, exec, s[6:7]
	s_cbranch_vccnz .LBB0_186
	v_ffbh_u32_e32 v194, v177
	v_min_u32_e32 v196, 32, v194
	v_lshlrev_b64 v[194:195], v196, v[176:177]
	v_min_u32_e32 v194, 1, v194
	v_or_b32_e32 v194, v195, v194
	v_cvt_f32_u32_e32 v194, v194
	v_sub_u32_e32 v195, 32, v196
	v_ldexp_f32 v194, v194, v195
	v_mul_f32_e32 v194, 0x33800000, v194
	v_fmamk_f32 v194, v194, 0x3a000000, v232
	v_rsq_f32_e32 v194, v194
	ds_write_b32 v190, v194
	s_branch .LBB0_186

.LBB0_208:
	s_mov_b32 m0, s51
	s_add_u32 s66, s34, 0x80
	s_addc_u32 s67, s35, 0
	ds_read_b128 v[188:191], v213 offset:49152
	ds_read_b128 v[192:195], v213 offset:50176
	ds_read_b128 v[196:199], v213 offset:51200
	ds_read_b128 v[206:209], v213 offset:52224
	ds_read_b128 v[214:217], v213 offset:53248
	ds_read_b128 v[218:221], v213 offset:54272
	ds_read_b128 v[222:225], v213 offset:55296
	ds_read_b128 v[226:229], v213 offset:56320
	global_load_lds_dwordx4 v4, s[66:67]
	s_mov_b32 m0, s52
	s_add_u32 s6, s34, 0x80080
	s_addc_u32 s7, s35, 0
	global_load_lds_dwordx4 v2, s[66:67]
	s_mov_b32 m0, s55
	s_add_u32 s98, s38, 0xfff80080
	s_addc_u32 s99, s39, -1
	global_load_lds_dwordx4 v4, s[6:7]
	s_mov_b32 m0, s56
	s_nop 0
	global_load_lds_dwordx4 v2, s[6:7]
	s_mov_b32 m0, s53
	s_nop 0
	global_load_lds_dwordx4 v168, s[98:99]
	s_mov_b32 m0, s54
	s_nop 0
	global_load_lds_dwordx4 v166, s[98:99]
	s_waitcnt vmcnt(8) lgkmcnt(0)
	s_barrier
	v_mfma_f32_16x16x32_bf16 v[18:21], v[158:161], v[188:191], v[18:21]
	v_mfma_f32_16x16x32_bf16 v[26:29], v[162:165], v[188:191], v[26:29]
	v_mfma_f32_16x16x32_bf16 v[34:37], v[158:161], v[196:199], v[34:37]
	v_mfma_f32_16x16x32_bf16 v[42:45], v[162:165], v[196:199], v[42:45]
	v_mfma_f32_16x16x32_bf16 v[180:183], v[158:161], v[214:217], v[50:53]
	v_mfma_f32_16x16x32_bf16 v[184:187], v[162:165], v[214:217], v[58:61]
	v_mfma_f32_16x16x32_bf16 v[158:161], v[158:161], v[222:225], v[62:65]
	v_mfma_f32_16x16x32_bf16 v[162:165], v[162:165], v[222:225], v[66:69]
	v_mfma_f32_16x16x32_bf16 v[66:69], v[150:153], v[192:195], v[18:21]
	v_mfma_f32_16x16x32_bf16 v[62:65], v[154:157], v[192:195], v[26:29]
	v_mfma_f32_16x16x32_bf16 v[58:61], v[150:153], v[206:209], v[34:37]
	v_mfma_f32_16x16x32_bf16 v[50:53], v[154:157], v[206:209], v[42:45]
	v_mfma_f32_16x16x32_bf16 v[42:45], v[150:153], v[218:221], v[180:183]
	v_mfma_f32_16x16x32_bf16 v[34:37], v[154:157], v[218:221], v[184:187]
	v_mfma_f32_16x16x32_bf16 v[26:29], v[150:153], v[226:229], v[158:161]
	v_mfma_f32_16x16x32_bf16 v[18:21], v[154:157], v[226:229], v[162:165]
	v_mfma_f32_16x16x32_bf16 v[6:9], v[142:145], v[188:191], v[6:9]
	v_mfma_f32_16x16x32_bf16 v[10:13], v[146:149], v[188:191], v[10:13]
	v_mfma_f32_16x16x32_bf16 v[14:17], v[142:145], v[196:199], v[14:17]
	v_mfma_f32_16x16x32_bf16 v[22:25], v[146:149], v[196:199], v[22:25]
	v_mfma_f32_16x16x32_bf16 v[150:153], v[142:145], v[214:217], v[30:33]
	v_mfma_f32_16x16x32_bf16 v[154:157], v[146:149], v[214:217], v[38:41]
	v_mfma_f32_16x16x32_bf16 v[142:145], v[142:145], v[222:225], v[46:49]
	v_mfma_f32_16x16x32_bf16 v[146:149], v[146:149], v[222:225], v[54:57]
	v_mfma_f32_16x16x32_bf16 v[54:57], v[134:137], v[192:195], v[6:9]
	v_mfma_f32_16x16x32_bf16 v[46:49], v[138:141], v[192:195], v[10:13]
	v_mfma_f32_16x16x32_bf16 v[38:41], v[134:137], v[206:209], v[14:17]
	v_mfma_f32_16x16x32_bf16 v[30:33], v[138:141], v[206:209], v[22:25]
	v_mfma_f32_16x16x32_bf16 v[22:25], v[134:137], v[218:221], v[150:153]
	v_mfma_f32_16x16x32_bf16 v[14:17], v[138:141], v[218:221], v[154:157]
	v_mfma_f32_16x16x32_bf16 v[10:13], v[134:137], v[226:229], v[142:145]
	v_mfma_f32_16x16x32_bf16 v[6:9], v[138:141], v[226:229], v[146:149]
	s_barrier
	s_add_i32 s65, s65, 2
	s_add_u32 s8, s8, 0x100
	s_addc_u32 s9, s9, 0
	s_add_u32 s31, s31, 0x100
	s_addc_u32 s64, s64, 0
	s_cmp_gt_u32 s65, 29
	s_cbranch_scc1 .LBB0_213

.LBB0_211:
	s_add_u32 s38, s8, 0xfff80080
	s_addc_u32 s39, s9, -1
	s_and_b64 s[34:35], s[34:35], exec
	s_cselect_b32 s39, s25, s39
	s_cselect_b32 s38, s62, s38
	s_cselect_b32 s35, s23, s64
	s_cselect_b32 s34, s63, s31
	s_add_i32 s66, 0, 0x10000
	s_add_i32 s68, 0, 0x14000
	ds_read_b128 v[134:137], v173
	ds_read_b128 v[138:141], v173 offset:1024
	ds_read_b128 v[142:145], v173 offset:2048
	ds_read_b128 v[146:149], v173 offset:3072
	ds_read_b128 v[150:153], v173 offset:16384
	ds_read_b128 v[154:157], v173 offset:17408
	ds_read_b128 v[158:161], v173 offset:18432
	ds_read_b128 v[162:165], v173 offset:19456
	s_add_i32 m0, s33, 0xc000
	ds_read_b128 v[180:183], v213
	ds_read_b128 v[184:187], v213 offset:1024
	ds_read_b128 v[188:191], v213 offset:2048
	ds_read_b128 v[192:195], v213 offset:3072
	ds_read_b128 v[196:199], v213 offset:4096
	ds_read_b128 v[206:209], v213 offset:5120
	ds_read_b128 v[214:217], v213 offset:6144
	ds_read_b128 v[218:221], v213 offset:7168
	global_load_lds_dwordx4 v172, s[8:9]
	s_add_i32 m0, s33, 0xe000
	s_nop 0
	global_load_lds_dwordx4 v174, s[8:9]
	s_waitcnt vmcnt(8) lgkmcnt(0)
	s_barrier
	v_mfma_f32_16x16x32_bf16 v[130:133], v[134:137], v[180:183], v[130:133]
	v_mfma_f32_16x16x32_bf16 v[126:129], v[142:145], v[180:183], v[126:129]
	v_mfma_f32_16x16x32_bf16 v[122:125], v[134:137], v[188:191], v[122:125]
	v_mfma_f32_16x16x32_bf16 v[114:117], v[142:145], v[188:191], v[114:117]
	v_mfma_f32_16x16x32_bf16 v[106:109], v[134:137], v[196:199], v[106:109]
	v_mfma_f32_16x16x32_bf16 v[98:101], v[142:145], v[196:199], v[98:101]
	v_mfma_f32_16x16x32_bf16 v[90:93], v[134:137], v[214:217], v[90:93]
	v_mfma_f32_16x16x32_bf16 v[82:85], v[142:145], v[214:217], v[82:85]
	v_mfma_f32_16x16x32_bf16 v[130:133], v[138:141], v[184:187], v[130:133]
	v_mfma_f32_16x16x32_bf16 v[126:129], v[146:149], v[184:187], v[126:129]
	v_mfma_f32_16x16x32_bf16 v[122:125], v[138:141], v[192:195], v[122:125]
	v_mfma_f32_16x16x32_bf16 v[114:117], v[146:149], v[192:195], v[114:117]
	v_mfma_f32_16x16x32_bf16 v[106:109], v[138:141], v[206:209], v[106:109]
	v_mfma_f32_16x16x32_bf16 v[98:101], v[146:149], v[206:209], v[98:101]
	v_mfma_f32_16x16x32_bf16 v[90:93], v[138:141], v[218:221], v[90:93]
	v_mfma_f32_16x16x32_bf16 v[82:85], v[146:149], v[218:221], v[82:85]
	v_mfma_f32_16x16x32_bf16 v[118:121], v[150:153], v[180:183], v[118:121]
	v_mfma_f32_16x16x32_bf16 v[110:113], v[158:161], v[180:183], v[110:113]
	v_mfma_f32_16x16x32_bf16 v[102:105], v[150:153], v[188:191], v[102:105]
	v_mfma_f32_16x16x32_bf16 v[94:97], v[158:161], v[188:191], v[94:97]
	v_mfma_f32_16x16x32_bf16 v[86:89], v[150:153], v[196:199], v[86:89]
	v_mfma_f32_16x16x32_bf16 v[78:81], v[158:161], v[196:199], v[78:81]
	v_mfma_f32_16x16x32_bf16 v[74:77], v[150:153], v[214:217], v[74:77]
	v_mfma_f32_16x16x32_bf16 v[70:73], v[158:161], v[214:217], v[70:73]
	v_mfma_f32_16x16x32_bf16 v[118:121], v[154:157], v[184:187], v[118:121]
	v_mfma_f32_16x16x32_bf16 v[110:113], v[162:165], v[184:187], v[110:113]
	v_mfma_f32_16x16x32_bf16 v[102:105], v[154:157], v[192:195], v[102:105]
	v_mfma_f32_16x16x32_bf16 v[94:97], v[162:165], v[192:195], v[94:97]
	v_mfma_f32_16x16x32_bf16 v[86:89], v[154:157], v[206:209], v[86:89]
	v_mfma_f32_16x16x32_bf16 v[78:81], v[162:165], v[206:209], v[78:81]
	v_mfma_f32_16x16x32_bf16 v[74:77], v[154:157], v[218:221], v[74:77]
	v_mfma_f32_16x16x32_bf16 v[70:73], v[162:165], v[218:221], v[70:73]
	s_barrier
	s_add_i32 s66, s66, s45
	s_mov_b32 m0, s66
	ds_read_b128 v[188:191], v213 offset:16384
	ds_read_b128 v[192:195], v213 offset:17408
	ds_read_b128 v[196:199], v213 offset:18432
	ds_read_b128 v[206:209], v213 offset:19456
	ds_read_b128 v[214:217], v213 offset:20480
	ds_read_b128 v[218:221], v213 offset:21504
	ds_read_b128 v[222:225], v213 offset:22528
	ds_read_b128 v[226:229], v213 offset:23552
	global_load_lds_dwordx4 v4, s[34:35]
	s_add_i32 m0, s66, 0x2000
	s_add_u32 s66, s34, 0x80000
	s_addc_u32 s67, s35, 0
	global_load_lds_dwordx4 v2, s[34:35]
	s_add_i32 s68, s68, s45
	s_mov_b32 m0, s68
	s_nop 0
	global_load_lds_dwordx4 v4, s[66:67]
	s_add_i32 m0, s68, 0x2000
	s_nop 0
	global_load_lds_dwordx4 v2, s[66:67]
	s_mov_b32 m0, s33
	s_nop 0
	global_load_lds_dwordx4 v168, s[38:39]
	s_mov_b32 m0, s46
	s_nop 0
	global_load_lds_dwordx4 v166, s[38:39]
	s_waitcnt vmcnt(8) lgkmcnt(0)
	s_barrier
	v_mfma_f32_16x16x32_bf16 v[66:69], v[134:137], v[188:191], v[66:69]
	v_mfma_f32_16x16x32_bf16 v[62:65], v[142:145], v[188:191], v[62:65]
	v_mfma_f32_16x16x32_bf16 v[58:61], v[134:137], v[196:199], v[58:61]
	v_mfma_f32_16x16x32_bf16 v[50:53], v[142:145], v[196:199], v[50:53]
	v_mfma_f32_16x16x32_bf16 v[248:251], v[134:137], v[214:217], v[42:45]
	v_mfma_f32_16x16x32_bf16 v[236:239], v[142:145], v[214:217], v[34:37]
	v_mfma_f32_16x16x32_bf16 v[134:137], v[134:137], v[222:225], v[26:29]
	v_mfma_f32_16x16x32_bf16 v[142:145], v[142:145], v[222:225], v[18:21]
	v_mfma_f32_16x16x32_bf16 v[18:21], v[138:141], v[192:195], v[66:69]
	v_mfma_f32_16x16x32_bf16 v[26:29], v[146:149], v[192:195], v[62:65]
	v_mfma_f32_16x16x32_bf16 v[34:37], v[138:141], v[206:209], v[58:61]
	v_mfma_f32_16x16x32_bf16 v[42:45], v[146:149], v[206:209], v[50:53]
	v_mfma_f32_16x16x32_bf16 v[50:53], v[138:141], v[218:221], v[248:251]
	v_mfma_f32_16x16x32_bf16 v[58:61], v[146:149], v[218:221], v[236:239]
	v_mfma_f32_16x16x32_bf16 v[62:65], v[138:141], v[226:229], v[134:137]
	v_mfma_f32_16x16x32_bf16 v[66:69], v[146:149], v[226:229], v[142:145]
	v_mfma_f32_16x16x32_bf16 v[54:57], v[150:153], v[188:191], v[54:57]
	v_mfma_f32_16x16x32_bf16 v[46:49], v[158:161], v[188:191], v[46:49]
	v_mfma_f32_16x16x32_bf16 v[38:41], v[150:153], v[196:199], v[38:41]
	v_mfma_f32_16x16x32_bf16 v[30:33], v[158:161], v[196:199], v[30:33]
	v_mfma_f32_16x16x32_bf16 v[134:137], v[150:153], v[214:217], v[22:25]
	v_mfma_f32_16x16x32_bf16 v[138:141], v[158:161], v[214:217], v[14:17]
	v_mfma_f32_16x16x32_bf16 v[142:145], v[150:153], v[222:225], v[10:13]
	v_mfma_f32_16x16x32_bf16 v[146:149], v[158:161], v[222:225], v[6:9]
	v_mfma_f32_16x16x32_bf16 v[6:9], v[154:157], v[192:195], v[54:57]
	v_mfma_f32_16x16x32_bf16 v[10:13], v[162:165], v[192:195], v[46:49]
	v_mfma_f32_16x16x32_bf16 v[14:17], v[154:157], v[206:209], v[38:41]
	v_mfma_f32_16x16x32_bf16 v[22:25], v[162:165], v[206:209], v[30:33]
	v_mfma_f32_16x16x32_bf16 v[30:33], v[154:157], v[218:221], v[134:137]
	v_mfma_f32_16x16x32_bf16 v[38:41], v[162:165], v[218:221], v[138:141]
	v_mfma_f32_16x16x32_bf16 v[46:49], v[154:157], v[226:229], v[142:145]
	v_mfma_f32_16x16x32_bf16 v[54:57], v[162:165], v[226:229], v[146:149]
	s_barrier
	ds_read_b128 v[158:161], v173 offset:32768
	ds_read_b128 v[150:153], v173 offset:33792
	ds_read_b128 v[162:165], v173 offset:34816
	ds_read_b128 v[154:157], v173 offset:35840
	ds_read_b128 v[142:145], v173 offset:49152
	ds_read_b128 v[134:137], v173 offset:50176
	ds_read_b128 v[146:149], v173 offset:51200
	ds_read_b128 v[138:141], v173 offset:52224
	s_add_u32 s38, s38, 0x80000
	s_addc_u32 s39, s39, 0
	s_mov_b32 m0, s47
	ds_read_b128 v[188:191], v213 offset:32768
	ds_read_b128 v[192:195], v213 offset:33792
	ds_read_b128 v[196:199], v213 offset:34816
	ds_read_b128 v[206:209], v213 offset:35840
	ds_read_b128 v[214:217], v213 offset:36864
	ds_read_b128 v[218:221], v213 offset:37888
	ds_read_b128 v[222:225], v213 offset:38912
	ds_read_b128 v[226:229], v213 offset:39936
	global_load_lds_dwordx4 v168, s[38:39]
	s_mov_b32 m0, s48
	s_nop 0
	global_load_lds_dwordx4 v166, s[38:39]
	s_waitcnt vmcnt(8) lgkmcnt(0)
	s_barrier
	v_mfma_f32_16x16x32_bf16 v[130:133], v[158:161], v[188:191], v[130:133]
	v_mfma_f32_16x16x32_bf16 v[126:129], v[162:165], v[188:191], v[126:129]
	v_mfma_f32_16x16x32_bf16 v[122:125], v[158:161], v[196:199], v[122:125]
	v_mfma_f32_16x16x32_bf16 v[114:117], v[162:165], v[196:199], v[114:117]
	v_mfma_f32_16x16x32_bf16 v[106:109], v[158:161], v[214:217], v[106:109]
	v_mfma_f32_16x16x32_bf16 v[98:101], v[162:165], v[214:217], v[98:101]
	v_mfma_f32_16x16x32_bf16 v[90:93], v[158:161], v[222:225], v[90:93]
	v_mfma_f32_16x16x32_bf16 v[82:85], v[162:165], v[222:225], v[82:85]
	v_mfma_f32_16x16x32_bf16 v[130:133], v[150:153], v[192:195], v[130:133]
	v_mfma_f32_16x16x32_bf16 v[126:129], v[154:157], v[192:195], v[126:129]
	v_mfma_f32_16x16x32_bf16 v[122:125], v[150:153], v[206:209], v[122:125]
	v_mfma_f32_16x16x32_bf16 v[114:117], v[154:157], v[206:209], v[114:117]
	v_mfma_f32_16x16x32_bf16 v[106:109], v[150:153], v[218:221], v[106:109]
	v_mfma_f32_16x16x32_bf16 v[98:101], v[154:157], v[218:221], v[98:101]
	v_mfma_f32_16x16x32_bf16 v[90:93], v[150:153], v[226:229], v[90:93]
	v_mfma_f32_16x16x32_bf16 v[82:85], v[154:157], v[226:229], v[82:85]
	v_mfma_f32_16x16x32_bf16 v[118:121], v[142:145], v[188:191], v[118:121]
	v_mfma_f32_16x16x32_bf16 v[110:113], v[146:149], v[188:191], v[110:113]
	v_mfma_f32_16x16x32_bf16 v[102:105], v[142:145], v[196:199], v[102:105]
	v_mfma_f32_16x16x32_bf16 v[94:97], v[146:149], v[196:199], v[94:97]
	v_mfma_f32_16x16x32_bf16 v[86:89], v[142:145], v[214:217], v[86:89]
	v_mfma_f32_16x16x32_bf16 v[78:81], v[146:149], v[214:217], v[78:81]
	v_mfma_f32_16x16x32_bf16 v[74:77], v[142:145], v[222:225], v[74:77]
	v_mfma_f32_16x16x32_bf16 v[70:73], v[146:149], v[222:225], v[70:73]
	v_mfma_f32_16x16x32_bf16 v[118:121], v[134:137], v[192:195], v[118:121]
	v_mfma_f32_16x16x32_bf16 v[110:113], v[138:141], v[192:195], v[110:113]
	v_mfma_f32_16x16x32_bf16 v[102:105], v[134:137], v[206:209], v[102:105]
	v_mfma_f32_16x16x32_bf16 v[94:97], v[138:141], v[206:209], v[94:97]
	v_mfma_f32_16x16x32_bf16 v[86:89], v[134:137], v[218:221], v[86:89]
	v_mfma_f32_16x16x32_bf16 v[78:81], v[138:141], v[218:221], v[78:81]
	v_mfma_f32_16x16x32_bf16 v[74:77], v[134:137], v[226:229], v[74:77]
	v_mfma_f32_16x16x32_bf16 v[70:73], v[138:141], v[226:229], v[70:73]
	s_barrier
	s_and_b64 vcc, exec, s[6:7]
	s_cbranch_vccnz .LBB0_208
	v_ffbh_u32_e32 v188, v177
	v_min_u32_e32 v190, 32, v188
	v_lshlrev_b64 v[188:189], v190, v[176:177]
	v_min_u32_e32 v188, 1, v188
	v_or_b32_e32 v188, v189, v188
	v_cvt_f32_u32_e32 v188, v188
	v_sub_u32_e32 v189, 32, v190
	v_ldexp_f32 v188, v188, v189
	v_mul_f32_e32 v188, 0x33800000, v188
	v_fmamk_f32 v188, v188, 0x3a000000, v232
	v_rsq_f32_e32 v188, v188
	ds_write_b32 v204, v188
	s_branch .LBB0_208

.LBB0_497:
	s_add_i32 s56, s30, 2
	s_add_u32 s57, s28, 0x80
	s_addc_u32 s31, s29, 0
	s_add_i32 s60, 0, 0x10000
	s_cmp_eq_u32 s48, s30
	s_cselect_b32 s31, s15, s31
	s_cselect_b32 s30, s14, s57
	s_cselect_b32 s59, s27, s55
	s_cselect_b32 s58, s26, s54
	s_add_i32 s57, 0, 0x14000
	ds_read_b128 v[134:137], v238
	ds_read_b128 v[138:141], v238 offset:1024
	ds_read_b128 v[142:145], v238 offset:2048
	ds_read_b128 v[146:149], v238 offset:3072
	ds_read_b128 v[150:153], v238 offset:16384
	ds_read_b128 v[154:157], v238 offset:17408
	ds_read_b128 v[158:161], v238 offset:18432
	ds_read_b128 v[162:165], v238 offset:19456
	s_add_i32 m0, s41, 0xc000
	ds_read_b128 v[166:169], v251
	ds_read_b128 v[170:173], v251 offset:1024
	ds_read_b128 v[174:177], v251 offset:2048
	ds_read_b128 v[178:181], v251 offset:3072
	ds_read_b128 v[182:185], v251 offset:4096
	ds_read_b128 v[186:189], v251 offset:5120
	ds_read_b128 v[190:193], v251 offset:6144
	ds_read_b128 v[194:197], v251 offset:7168
	global_load_lds_dwordx4 v224, s[28:29]
	s_add_i32 m0, s41, 0xe000
	s_nop 0
	global_load_lds_dwordx4 v226, s[28:29]
	s_waitcnt vmcnt(8) lgkmcnt(0)
	s_barrier
	v_mfma_f32_16x16x32_bf16 v[130:133], v[134:137], v[166:169], v[130:133]
	v_mfma_f32_16x16x32_bf16 v[126:129], v[142:145], v[166:169], v[126:129]
	v_mfma_f32_16x16x32_bf16 v[114:117], v[134:137], v[174:177], v[114:117]
	v_mfma_f32_16x16x32_bf16 v[110:113], v[142:145], v[174:177], v[110:113]
	v_mfma_f32_16x16x32_bf16 v[98:101], v[134:137], v[182:185], v[98:101]
	v_mfma_f32_16x16x32_bf16 v[94:97], v[142:145], v[182:185], v[94:97]
	v_mfma_f32_16x16x32_bf16 v[82:85], v[134:137], v[190:193], v[82:85]
	v_mfma_f32_16x16x32_bf16 v[78:81], v[142:145], v[190:193], v[78:81]
	v_mfma_f32_16x16x32_bf16 v[130:133], v[138:141], v[170:173], v[130:133]
	v_mfma_f32_16x16x32_bf16 v[126:129], v[146:149], v[170:173], v[126:129]
	v_mfma_f32_16x16x32_bf16 v[114:117], v[138:141], v[178:181], v[114:117]
	v_mfma_f32_16x16x32_bf16 v[110:113], v[146:149], v[178:181], v[110:113]
	v_mfma_f32_16x16x32_bf16 v[98:101], v[138:141], v[186:189], v[98:101]
	v_mfma_f32_16x16x32_bf16 v[94:97], v[146:149], v[186:189], v[94:97]
	v_mfma_f32_16x16x32_bf16 v[82:85], v[138:141], v[194:197], v[82:85]
	v_mfma_f32_16x16x32_bf16 v[78:81], v[146:149], v[194:197], v[78:81]
	v_mfma_f32_16x16x32_bf16 v[122:125], v[150:153], v[166:169], v[122:125]
	v_mfma_f32_16x16x32_bf16 v[118:121], v[158:161], v[166:169], v[118:121]
	v_mfma_f32_16x16x32_bf16 v[106:109], v[150:153], v[174:177], v[106:109]
	v_mfma_f32_16x16x32_bf16 v[102:105], v[158:161], v[174:177], v[102:105]
	v_mfma_f32_16x16x32_bf16 v[90:93], v[150:153], v[182:185], v[90:93]
	v_mfma_f32_16x16x32_bf16 v[86:89], v[158:161], v[182:185], v[86:89]
	v_mfma_f32_16x16x32_bf16 v[74:77], v[150:153], v[190:193], v[74:77]
	v_mfma_f32_16x16x32_bf16 v[70:73], v[158:161], v[190:193], v[70:73]
	v_mfma_f32_16x16x32_bf16 v[122:125], v[154:157], v[170:173], v[122:125]
	v_mfma_f32_16x16x32_bf16 v[118:121], v[162:165], v[170:173], v[118:121]
	v_mfma_f32_16x16x32_bf16 v[106:109], v[154:157], v[178:181], v[106:109]
	v_mfma_f32_16x16x32_bf16 v[102:105], v[162:165], v[178:181], v[102:105]
	v_mfma_f32_16x16x32_bf16 v[90:93], v[154:157], v[186:189], v[90:93]
	v_mfma_f32_16x16x32_bf16 v[86:89], v[162:165], v[186:189], v[86:89]
	v_mfma_f32_16x16x32_bf16 v[74:77], v[154:157], v[194:197], v[74:77]
	v_mfma_f32_16x16x32_bf16 v[70:73], v[162:165], v[194:197], v[70:73]
	s_barrier
	s_add_i32 s60, s60, s40
	s_mov_b32 m0, s60
	ds_read_b128 v[166:169], v251 offset:16384
	ds_read_b128 v[170:173], v251 offset:17408
	ds_read_b128 v[174:177], v251 offset:18432
	ds_read_b128 v[178:181], v251 offset:19456
	ds_read_b128 v[182:185], v251 offset:20480
	ds_read_b128 v[186:189], v251 offset:21504
	ds_read_b128 v[190:193], v251 offset:22528
	ds_read_b128 v[194:197], v251 offset:23552
	global_load_lds_dwordx4 v214, s[58:59]
	s_add_i32 m0, s60, 0x2000
	s_add_i32 s57, s57, s40
	global_load_lds_dwordx4 v2, s[58:59]
	s_add_u32 s58, s58, s76
	s_addc_u32 s59, s59, 0
	s_mov_b32 m0, s57
	s_nop 0
	global_load_lds_dwordx4 v214, s[58:59]
	s_add_i32 m0, s57, 0x2000
	s_nop 0
	global_load_lds_dwordx4 v2, s[58:59]
	s_mov_b32 m0, s41
	s_nop 0
	global_load_lds_dwordx4 v216, s[30:31]
	s_mov_b32 m0, s42
	s_nop 0
	global_load_lds_dwordx4 v212, s[30:31]
	s_waitcnt vmcnt(8) lgkmcnt(0)
	s_barrier
	v_mfma_f32_16x16x32_bf16 v[66:69], v[134:137], v[166:169], v[66:69]
	v_mfma_f32_16x16x32_bf16 v[62:65], v[142:145], v[166:169], v[62:65]
	v_mfma_f32_16x16x32_bf16 v[50:53], v[134:137], v[174:177], v[50:53]
	v_mfma_f32_16x16x32_bf16 v[46:49], v[142:145], v[174:177], v[46:49]
	v_mfma_f32_16x16x32_bf16 v[34:37], v[134:137], v[182:185], v[34:37]
	v_mfma_f32_16x16x32_bf16 v[30:33], v[142:145], v[182:185], v[30:33]
	v_mfma_f32_16x16x32_bf16 v[18:21], v[134:137], v[190:193], v[18:21]
	v_mfma_f32_16x16x32_bf16 v[14:17], v[142:145], v[190:193], v[14:17]
	v_mfma_f32_16x16x32_bf16 v[66:69], v[138:141], v[170:173], v[66:69]
	v_mfma_f32_16x16x32_bf16 v[62:65], v[146:149], v[170:173], v[62:65]
	v_mfma_f32_16x16x32_bf16 v[50:53], v[138:141], v[178:181], v[50:53]
	v_mfma_f32_16x16x32_bf16 v[46:49], v[146:149], v[178:181], v[46:49]
	v_mfma_f32_16x16x32_bf16 v[34:37], v[138:141], v[186:189], v[34:37]
	v_mfma_f32_16x16x32_bf16 v[30:33], v[146:149], v[186:189], v[30:33]
	v_mfma_f32_16x16x32_bf16 v[18:21], v[138:141], v[194:197], v[18:21]
	v_mfma_f32_16x16x32_bf16 v[14:17], v[146:149], v[194:197], v[14:17]
	v_mfma_f32_16x16x32_bf16 v[58:61], v[150:153], v[166:169], v[58:61]
	v_mfma_f32_16x16x32_bf16 v[54:57], v[158:161], v[166:169], v[54:57]
	v_mfma_f32_16x16x32_bf16 v[42:45], v[150:153], v[174:177], v[42:45]
	v_mfma_f32_16x16x32_bf16 v[38:41], v[158:161], v[174:177], v[38:41]
	v_mfma_f32_16x16x32_bf16 v[26:29], v[150:153], v[182:185], v[26:29]
	v_mfma_f32_16x16x32_bf16 v[22:25], v[158:161], v[182:185], v[22:25]
	v_mfma_f32_16x16x32_bf16 v[10:13], v[150:153], v[190:193], v[10:13]
	v_mfma_f32_16x16x32_bf16 v[6:9], v[158:161], v[190:193], v[6:9]
	v_mfma_f32_16x16x32_bf16 v[58:61], v[154:157], v[170:173], v[58:61]
	v_mfma_f32_16x16x32_bf16 v[54:57], v[162:165], v[170:173], v[54:57]
	v_mfma_f32_16x16x32_bf16 v[42:45], v[154:157], v[178:181], v[42:45]
	v_mfma_f32_16x16x32_bf16 v[38:41], v[162:165], v[178:181], v[38:41]
	v_mfma_f32_16x16x32_bf16 v[26:29], v[154:157], v[186:189], v[26:29]
	v_mfma_f32_16x16x32_bf16 v[22:25], v[162:165], v[186:189], v[22:25]
	v_mfma_f32_16x16x32_bf16 v[10:13], v[154:157], v[194:197], v[10:13]
	v_mfma_f32_16x16x32_bf16 v[6:9], v[162:165], v[194:197], v[6:9]
	s_barrier
	ds_read_b128 v[134:137], v238 offset:32768
	ds_read_b128 v[138:141], v238 offset:33792
	ds_read_b128 v[142:145], v238 offset:34816
	ds_read_b128 v[146:149], v238 offset:35840
	ds_read_b128 v[150:153], v238 offset:49152
	ds_read_b128 v[154:157], v238 offset:50176
	ds_read_b128 v[158:161], v238 offset:51200
	ds_read_b128 v[162:165], v238 offset:52224
	s_add_u32 s30, s30, s76
	s_addc_u32 s31, s31, 0
	s_mov_b32 m0, s43
	ds_read_b128 v[166:169], v251 offset:32768
	ds_read_b128 v[170:173], v251 offset:33792
	ds_read_b128 v[174:177], v251 offset:34816
	ds_read_b128 v[178:181], v251 offset:35840
	ds_read_b128 v[182:185], v251 offset:36864
	ds_read_b128 v[186:189], v251 offset:37888
	ds_read_b128 v[190:193], v251 offset:38912
	ds_read_b128 v[194:197], v251 offset:39936
	global_load_lds_dwordx4 v216, s[30:31]
	s_mov_b32 m0, s44
	s_nop 0
	global_load_lds_dwordx4 v212, s[30:31]
	s_waitcnt vmcnt(8) lgkmcnt(0)
	s_barrier
	v_mfma_f32_16x16x32_bf16 v[130:133], v[134:137], v[166:169], v[130:133]
	v_mfma_f32_16x16x32_bf16 v[126:129], v[142:145], v[166:169], v[126:129]
	v_mfma_f32_16x16x32_bf16 v[114:117], v[134:137], v[174:177], v[114:117]
	v_mfma_f32_16x16x32_bf16 v[110:113], v[142:145], v[174:177], v[110:113]
	v_mfma_f32_16x16x32_bf16 v[98:101], v[134:137], v[182:185], v[98:101]
	v_mfma_f32_16x16x32_bf16 v[94:97], v[142:145], v[182:185], v[94:97]
	v_mfma_f32_16x16x32_bf16 v[82:85], v[134:137], v[190:193], v[82:85]
	v_mfma_f32_16x16x32_bf16 v[78:81], v[142:145], v[190:193], v[78:81]
	v_mfma_f32_16x16x32_bf16 v[130:133], v[138:141], v[170:173], v[130:133]
	v_mfma_f32_16x16x32_bf16 v[126:129], v[146:149], v[170:173], v[126:129]
	v_mfma_f32_16x16x32_bf16 v[114:117], v[138:141], v[178:181], v[114:117]
	v_mfma_f32_16x16x32_bf16 v[110:113], v[146:149], v[178:181], v[110:113]
	v_mfma_f32_16x16x32_bf16 v[98:101], v[138:141], v[186:189], v[98:101]
	v_mfma_f32_16x16x32_bf16 v[94:97], v[146:149], v[186:189], v[94:97]
	v_mfma_f32_16x16x32_bf16 v[82:85], v[138:141], v[194:197], v[82:85]
	v_mfma_f32_16x16x32_bf16 v[78:81], v[146:149], v[194:197], v[78:81]
	v_mfma_f32_16x16x32_bf16 v[122:125], v[150:153], v[166:169], v[122:125]
	v_mfma_f32_16x16x32_bf16 v[118:121], v[158:161], v[166:169], v[118:121]
	v_mfma_f32_16x16x32_bf16 v[106:109], v[150:153], v[174:177], v[106:109]
	v_mfma_f32_16x16x32_bf16 v[102:105], v[158:161], v[174:177], v[102:105]
	v_mfma_f32_16x16x32_bf16 v[90:93], v[150:153], v[182:185], v[90:93]
	v_mfma_f32_16x16x32_bf16 v[86:89], v[158:161], v[182:185], v[86:89]
	v_mfma_f32_16x16x32_bf16 v[74:77], v[150:153], v[190:193], v[74:77]
	v_mfma_f32_16x16x32_bf16 v[70:73], v[158:161], v[190:193], v[70:73]
	v_mfma_f32_16x16x32_bf16 v[122:125], v[154:157], v[170:173], v[122:125]
	v_mfma_f32_16x16x32_bf16 v[118:121], v[162:165], v[170:173], v[118:121]
	v_mfma_f32_16x16x32_bf16 v[106:109], v[154:157], v[178:181], v[106:109]
	v_mfma_f32_16x16x32_bf16 v[102:105], v[162:165], v[178:181], v[102:105]
	v_mfma_f32_16x16x32_bf16 v[90:93], v[154:157], v[186:189], v[90:93]
	v_mfma_f32_16x16x32_bf16 v[86:89], v[162:165], v[186:189], v[86:89]
	v_mfma_f32_16x16x32_bf16 v[74:77], v[154:157], v[194:197], v[74:77]
	v_mfma_f32_16x16x32_bf16 v[70:73], v[162:165], v[194:197], v[70:73]
	s_barrier
	s_sub_u32 s98, s58, s76
	s_subb_u32 s99, s59, 0
	s_add_u32 s98, s98, 0x80
	s_addc_u32 s99, s99, 0
	s_add_i32 m0, s40, 0x18000
	ds_read_b128 v[166:169], v251 offset:49152
	ds_read_b128 v[170:173], v251 offset:50176
	ds_read_b128 v[174:177], v251 offset:51200
	ds_read_b128 v[178:181], v251 offset:52224
	ds_read_b128 v[182:185], v251 offset:53248
	ds_read_b128 v[186:189], v251 offset:54272
	ds_read_b128 v[190:193], v251 offset:55296
	ds_read_b128 v[194:197], v251 offset:56320
	global_load_lds_dwordx4 v214, s[98:99]
	s_add_i32 m0, s40, 0x1a000
	s_add_u32 s58, s58, 0x80
	s_addc_u32 s59, s59, 0
	global_load_lds_dwordx4 v2, s[98:99]
	s_add_i32 m0, s40, 0x1c000
	s_sub_u32 s30, s30, s76
	s_subb_u32 s31, s31, 0
	global_load_lds_dwordx4 v214, s[58:59]
	s_add_i32 m0, s40, 0x1e000
	s_add_u32 s30, s30, 0x80
	s_addc_u32 s31, s31, 0
	global_load_lds_dwordx4 v2, s[58:59]
	s_mov_b32 m0, s45
	s_nop 0
	global_load_lds_dwordx4 v216, s[30:31]
	s_mov_b32 m0, s46
	s_nop 0
	global_load_lds_dwordx4 v212, s[30:31]
	s_waitcnt vmcnt(8) lgkmcnt(0)
	s_barrier
	v_mfma_f32_16x16x32_bf16 v[66:69], v[134:137], v[166:169], v[66:69]
	v_mfma_f32_16x16x32_bf16 v[62:65], v[142:145], v[166:169], v[62:65]
	v_mfma_f32_16x16x32_bf16 v[50:53], v[134:137], v[174:177], v[50:53]
	v_mfma_f32_16x16x32_bf16 v[46:49], v[142:145], v[174:177], v[46:49]
	v_mfma_f32_16x16x32_bf16 v[34:37], v[134:137], v[182:185], v[34:37]
	v_mfma_f32_16x16x32_bf16 v[30:33], v[142:145], v[182:185], v[30:33]
	v_mfma_f32_16x16x32_bf16 v[18:21], v[134:137], v[190:193], v[18:21]
	v_mfma_f32_16x16x32_bf16 v[14:17], v[142:145], v[190:193], v[14:17]
	v_mfma_f32_16x16x32_bf16 v[66:69], v[138:141], v[170:173], v[66:69]
	v_mfma_f32_16x16x32_bf16 v[62:65], v[146:149], v[170:173], v[62:65]
	v_mfma_f32_16x16x32_bf16 v[50:53], v[138:141], v[178:181], v[50:53]
	v_mfma_f32_16x16x32_bf16 v[46:49], v[146:149], v[178:181], v[46:49]
	v_mfma_f32_16x16x32_bf16 v[34:37], v[138:141], v[186:189], v[34:37]
	v_mfma_f32_16x16x32_bf16 v[30:33], v[146:149], v[186:189], v[30:33]
	v_mfma_f32_16x16x32_bf16 v[18:21], v[138:141], v[194:197], v[18:21]
	v_mfma_f32_16x16x32_bf16 v[14:17], v[146:149], v[194:197], v[14:17]
	v_mfma_f32_16x16x32_bf16 v[58:61], v[150:153], v[166:169], v[58:61]
	v_mfma_f32_16x16x32_bf16 v[54:57], v[158:161], v[166:169], v[54:57]
	v_mfma_f32_16x16x32_bf16 v[42:45], v[150:153], v[174:177], v[42:45]
	v_mfma_f32_16x16x32_bf16 v[38:41], v[158:161], v[174:177], v[38:41]
	v_mfma_f32_16x16x32_bf16 v[26:29], v[150:153], v[182:185], v[26:29]
	v_mfma_f32_16x16x32_bf16 v[22:25], v[158:161], v[182:185], v[22:25]
	v_mfma_f32_16x16x32_bf16 v[10:13], v[150:153], v[190:193], v[10:13]
	v_mfma_f32_16x16x32_bf16 v[6:9], v[158:161], v[190:193], v[6:9]
	v_mfma_f32_16x16x32_bf16 v[58:61], v[154:157], v[170:173], v[58:61]
	v_mfma_f32_16x16x32_bf16 v[54:57], v[162:165], v[170:173], v[54:57]
	v_mfma_f32_16x16x32_bf16 v[42:45], v[154:157], v[178:181], v[42:45]
	v_mfma_f32_16x16x32_bf16 v[38:41], v[162:165], v[178:181], v[38:41]
	v_mfma_f32_16x16x32_bf16 v[26:29], v[154:157], v[186:189], v[26:29]
	v_mfma_f32_16x16x32_bf16 v[22:25], v[162:165], v[186:189], v[22:25]
	v_mfma_f32_16x16x32_bf16 v[10:13], v[154:157], v[194:197], v[10:13]
	v_mfma_f32_16x16x32_bf16 v[6:9], v[162:165], v[194:197], v[6:9]
	s_barrier
	s_add_u32 s28, s28, 0x100
	s_addc_u32 s29, s29, 0
	s_add_u32 s54, s54, 0x100
	s_addc_u32 s55, s55, 0
	s_cmp_ge_u32 s56, s47
	s_mov_b32 s30, s56
	s_cbranch_scc0 .LBB0_497
	s_and_b64 vcc, exec, s[24:25]
	s_cbranch_vccz .LBB0_500
	s_barrier
